# v39 + sc1 on EVMIX y stores and attention O stores
# baseline (speedup 1.0000x reference)
; #define LAS __attribute__((address_space(3)))
; __device__ __forceinline__ unsigned pk2(float lo, float hi) { const f32x2_t v = {lo, hi}; const bf16x2_t b = __builtin_convertvector(v, bf16x2_t); return __builtin_bit_cast(unsigned, b); }
; template <bool MOBA>
; __device__ __forceinline__ void attn_unit(unsigned char* lds, LAS unsigned char* lds3, const Params& p, int b, int h, int qb) {
;     ...
;     for (int jb = 0; jb < 2; ++jb) { float l = lrow[jb]; l += __shfl_xor(l, 16); l += __shfl_xor(l, 32);
;         if (MOBA) { const LAS float* st = pst + (qloc + 16 * jb) * 68; l = st[64];
; #pragma unroll
;             for (int db = 0; db < 4; ++db) o[db][jb] = *(const LAS f32x4*)(st + 32 * (db >> 1) + 8 * fq + 4 * (db & 1)); }
;         const float inv = 1.0f / l;
;         bf16_t* op = Og + (qrow0 + 16 * jb + fr) * DM + hcol + 8 * fq;
; #pragma unroll
;         for (int dp = 0; dp < 2; ++dp) { const f32x4 v0 = o[2 * dp][jb] * inv, v1 = o[2 * dp + 1][jb] * inv; u32x4 wv; wv.x = pk2(v0[0], v0[1]); wv.y = pk2(v0[2], v0[3]); wv.z = pk2(v1[0], v1[1]); wv.w = pk2(v1[2], v1[3]); *(u32x4*)(op + 32 * dp) = wv; } }
.LBB0_359:
	ds_bpermute_b32 v1, v117, v111
	s_add_u32 s4, s80, s82
	s_waitcnt vmcnt(3)
	v_lshlrev_b32_e32 v2, 1, v114
	v_mov_b32_e32 v3, v0
	s_addc_u32 s5, s81, 0
	s_waitcnt lgkmcnt(0)
	v_add_f32_e32 v1, v111, v1
	ds_bpermute_b32 v4, v118, v1
	v_lshl_add_u64 v[6:7], s[4:5], 0, v[2:3]
	v_lshl_add_u64 v[8:9], v[6:7], 0, v[108:109]
	s_mov_b32 s48, 0xfffc0000
	v_readlane_b32 s50, v255, 35
	s_waitcnt lgkmcnt(0)
	v_add_f32_e32 v1, v1, v4
	v_div_scale_f32 v2, s[4:5], v1, v1, 1.0
	v_rcp_f32_e32 v3, v2
	v_div_scale_f32 v4, vcc, 1.0, v1, 1.0
	v_readlane_b32 s88, v255, 31
	v_fma_f32 v5, -v2, v3, 1.0
	v_fmac_f32_e32 v3, v5, v3
	v_mul_f32_e32 v5, v4, v3
	v_fma_f32 v10, -v2, v5, v4
	v_fmac_f32_e32 v5, v10, v3
	v_fma_f32 v2, -v2, v5, v4
	v_div_fmas_f32 v2, v2, v3, v5
	v_div_fixup_f32 v10, v2, v1, 1.0
	ds_bpermute_b32 v1, v117, v110
	v_pk_mul_f32 v[4:5], v[72:73], v[10:11] op_sel_hi:[1,0]
	v_pk_mul_f32 v[2:3], v[70:71], v[10:11] op_sel_hi:[1,0]
	s_waitcnt vmcnt(2)
	v_pk_mul_f32 v[14:15], v[66:67], v[10:11] op_sel_hi:[1,0]
	v_cvt_pk_bf16_f32 v2, v2, v3
	s_waitcnt lgkmcnt(0)
	v_add_f32_e32 v1, v110, v1
	v_cvt_pk_bf16_f32 v3, v4, v5
	v_cvt_pk_bf16_f32 v4, v14, v15
	ds_bpermute_b32 v14, v118, v1
	v_pk_mul_f32 v[12:13], v[68:69], v[10:11] op_sel_hi:[1,0]
	v_readlane_b32 s52, v255, 33
	v_cvt_pk_bf16_f32 v5, v12, v13
	global_store_dwordx4 v[8:9], v[2:5], off sc1
	s_waitcnt lgkmcnt(0)
	v_add_f32_e32 v1, v1, v14
	v_div_scale_f32 v14, s[4:5], v1, v1, 1.0
	v_rcp_f32_e32 v15, v14
	v_pk_mul_f32 v[4:5], v[64:65], v[10:11] op_sel_hi:[1,0]
	v_pk_mul_f32 v[2:3], v[62:63], v[10:11] op_sel_hi:[1,0]
	v_pk_mul_f32 v[12:13], v[60:61], v[10:11] op_sel_hi:[1,0]
	v_pk_mul_f32 v[10:11], v[58:59], v[10:11] op_sel_hi:[1,0]
	v_cvt_pk_bf16_f32 v2, v2, v3
	v_cvt_pk_bf16_f32 v3, v4, v5
	v_cvt_pk_bf16_f32 v4, v10, v11
	v_cvt_pk_bf16_f32 v5, v12, v13
	global_store_dwordx4 v[8:9], v[2:5], off offset:64 sc1
	v_lshl_add_u64 v[10:11], v[6:7], 0, v[106:107]
	v_readlane_b32 s73, v254, 2
	v_fma_f32 v2, -v14, v15, 1.0
	v_fmac_f32_e32 v15, v2, v15
	v_div_scale_f32 v2, vcc, 1.0, v1, 1.0
	v_mul_f32_e32 v3, v2, v15
	v_fma_f32 v4, -v14, v3, v2
	v_fmac_f32_e32 v3, v4, v15
	v_fma_f32 v2, -v14, v3, v2
	v_div_fmas_f32 v2, v2, v15, v3
	v_div_fixup_f32 v12, v2, v1, 1.0
	v_pk_mul_f32 v[4:5], v[56:57], v[12:13] op_sel_hi:[1,0]
	v_pk_mul_f32 v[2:3], v[54:55], v[12:13] op_sel_hi:[1,0]
	v_pk_mul_f32 v[6:7], v[52:53], v[12:13] op_sel_hi:[1,0]
	v_pk_mul_f32 v[8:9], v[50:51], v[12:13] op_sel_hi:[1,0]
	v_cvt_pk_bf16_f32 v2, v2, v3
	v_cvt_pk_bf16_f32 v3, v4, v5
	v_cvt_pk_bf16_f32 v4, v8, v9
	v_cvt_pk_bf16_f32 v5, v6, v7
	global_store_dwordx4 v[10:11], v[2:5], off sc1
	v_pk_mul_f32 v[8:9], v[44:45], v[12:13] op_sel_hi:[1,0]
	v_pk_mul_f32 v[6:7], v[42:43], v[12:13] op_sel_hi:[1,0]
	v_pk_mul_f32 v[4:5], v[48:49], v[12:13] op_sel_hi:[1,0]
	v_pk_mul_f32 v[2:3], v[46:47], v[12:13] op_sel_hi:[1,0]
	s_mov_b32 s79, s3
	v_readlane_b32 s82, v255, 9
	s_movk_i32 s83, 0x161
	s_movk_i32 s91, 0x100
	s_movk_i32 s59, 0x1ff
	s_mov_b32 s60, 0xf800000
	v_readlane_b32 s61, v255, 5
	s_movk_i32 s62, 0x110
	v_readlane_b32 s63, v255, 12
	s_mov_b64 s[64:65], 0x800
	s_mov_b32 s49, -1
	v_readlane_b32 s94, v255, 8
	s_mov_b64 s[66:67], 0x8000
	v_readlane_b32 s51, v255, 36
	v_readlane_b32 s89, v255, 32
	v_readlane_b32 s53, v255, 34
.LBB0_360:
	s_add_i32 s95, s95, s78
	s_add_i32 s2, s2, s78
	v_cvt_pk_bf16_f32 v2, v2, v3
	v_cvt_pk_bf16_f32 v3, v4, v5
	v_cvt_pk_bf16_f32 v4, v6, v7
	v_cvt_pk_bf16_f32 v5, v8, v9
	s_cmpk_lt_i32 s95, 0x800
	s_movk_i32 s84, 0x1600
	global_store_dwordx4 v[10:11], v[2:5], off offset:64 sc1
	s_cbranch_scc0 .LBB0_555

; __device__ __forceinline__ unsigned pk2(float lo, float hi) { const f32x2_t v = {lo, hi}; const bf16x2_t b = __builtin_convertvector(v, bf16x2_t); return __builtin_bit_cast(unsigned, b); }
; __device__ __forceinline__ void phase_evmix(const Params& p, unsigned char* lds, int e) {
;     ...
;             for (int k = 0; k < 4; ++k) { const int it = tid + k * NTHREADS; const int r = it >> 4, ch = it & 15; const int pos = pos0 + r;
;                 float sum[8];
; #pragma unroll
;                 for (int j = 0; j < 8; ++j) sum[j] = 0.f;
;                 for (int i = 0; i < win; ++i) { const u32x4 v = *(const u32x4*)(Zp + (r + 15 - i) * 128 + ch * 8);
; #pragma unroll
;                     for (int j = 0; j < 4; ++j) { sum[2 * j] += bf_lo(v[j]); sum[2 * j + 1] += bf_hi(v[j]); } }
;                 const u32x4 xv = *(const u32x4*)(Zp + (r + 15) * 128 + ch * 8); const float inv = 1.0f / (float)((pos + 1 < win) ? pos + 1 : win);
;                 u32x4 w;
;                 w.x = pk2(sum[0] * inv - bf_lo(xv[0]), sum[1] * inv - bf_hi(xv[0])); w.y = pk2(sum[2] * inv - bf_lo(xv[1]), sum[3] * inv - bf_hi(xv[1]));
;                 w.z = pk2(sum[4] * inv - bf_lo(xv[2]), sum[5] * inv - bf_hi(xv[2])); w.w = pk2(sum[6] * inv - bf_lo(xv[3]), sum[7] * inv - bf_hi(xv[3]));
;                 *(u32x4*)(Pl + r * 136 + ch * 8) = w; }
;             __syncthreads();
.LBB0_956:
	ds_read_b128 v[214:217], v1
	s_add_i32 s33, s33, -1
	v_add_u32_e32 v1, 0xffffff00, v1
	s_cmp_lg_u32 s33, 0
	s_waitcnt lgkmcnt(0)
	v_lshlrev_b32_e32 v170, 16, v214
	v_and_b32_e32 v171, 0xffff0000, v214
	v_pk_add_f32 v[182:183], v[182:183], v[170:171]
	v_lshlrev_b32_e32 v170, 16, v215
	v_and_b32_e32 v171, 0xffff0000, v215
	v_pk_add_f32 v[180:181], v[180:181], v[170:171]
	v_lshlrev_b32_e32 v170, 16, v216
	v_and_b32_e32 v171, 0xffff0000, v216
	v_pk_add_f32 v[172:173], v[172:173], v[170:171]
	v_lshlrev_b32_e32 v170, 16, v217
	v_and_b32_e32 v171, 0xffff0000, v217
	v_pk_add_f32 v[2:3], v[2:3], v[170:171]
	s_cbranch_scc1 .LBB0_956
	v_add_u32_e32 v1, s4, v168
	v_min_i32_e32 v1, s5, v1
	v_cvt_f32_i32_e32 v1, v1
	ds_read_b128 v[214:217], v196 offset:3840
	s_mov_b64 s[36:37], 0
	v_div_scale_f32 v170, s[4:5], v1, v1, 1.0
	v_rcp_f32_e32 v171, v170
	s_nop 0
	v_fma_f32 v218, -v170, v171, 1.0
	v_fmac_f32_e32 v171, v218, v171
	v_div_scale_f32 v218, vcc, 1.0, v1, 1.0
	v_mul_f32_e32 v219, v218, v171
	v_fma_f32 v220, -v170, v219, v218
	v_fmac_f32_e32 v219, v220, v171
	v_fma_f32 v170, -v170, v219, v218
	v_div_fmas_f32 v170, v170, v171, v219
	v_div_fixup_f32 v170, v170, v1, 1.0
	s_waitcnt lgkmcnt(0)
	v_lshlrev_b32_e32 v218, 16, v214
	v_and_b32_e32 v219, 0xffff0000, v214
	v_pk_fma_f32 v[182:183], v[170:171], v[182:183], v[218:219] op_sel_hi:[0,1,1] neg_lo:[0,0,1] neg_hi:[0,0,1]
	v_cvt_pk_bf16_f32 v214, v182, v183
	v_lshlrev_b32_e32 v182, 16, v215
	v_and_b32_e32 v183, 0xffff0000, v215
	v_pk_fma_f32 v[180:181], v[170:171], v[180:181], v[182:183] op_sel_hi:[0,1,1] neg_lo:[0,0,1] neg_hi:[0,0,1]
	v_cvt_pk_bf16_f32 v215, v180, v181
	v_lshlrev_b32_e32 v180, 16, v216
	v_and_b32_e32 v181, 0xffff0000, v216
	v_pk_fma_f32 v[172:173], v[170:171], v[172:173], v[180:181] op_sel_hi:[0,1,1] neg_lo:[0,0,1] neg_hi:[0,0,1]
	v_cvt_pk_bf16_f32 v216, v172, v173
	v_lshlrev_b32_e32 v172, 16, v217
	v_and_b32_e32 v173, 0xffff0000, v217
	v_pk_fma_f32 v[2:3], v[170:171], v[2:3], v[172:173] op_sel_hi:[0,1,1] neg_lo:[0,0,1] neg_hi:[0,0,1]
	v_cvt_pk_bf16_f32 v217, v2, v3
	v_add_u32_e32 v1, v185, v169
	ds_write_b128 v1, v[214:217] offset:40960
	s_waitcnt lgkmcnt(0)
	s_barrier
; __device__ __forceinline__ unsigned pk2(float lo, float hi) { const f32x2_t v = {lo, hi}; const bf16x2_t b = __builtin_convertvector(v, bf16x2_t); return __builtin_bit_cast(unsigned, b); }
; __device__ __forceinline__ void phase_evmix(const Params& p, unsigned char* lds, int e) {
;     ...
;             f32x4 acc[8];
; #pragma unroll
;             for (int nb = 0; nb < 8; ++nb) acc[nb] = (f32x4){0.f, 0.f, 0.f, 0.f};
; #pragma unroll
;             for (int ks = 0; ks < 4; ++ks) { const bf16x8 a = *(const bf16x8*)(Pl + (16 * wave + fr) * 136 + 32 * ks + 8 * fq);
; #pragma unroll
;                 for (int nb = 0; nb < 8; ++nb) { const bf16x8 b = *(const bf16x8*)(Bl + (16 * nb + fr) * 136 + 32 * ks + 8 * fq); acc[nb] = __builtin_amdgcn_mfma_f32_16x16x32_bf16(b, a, acc[nb], 0, 0, 0); } }
;             const int row = rt * 128 + 16 * wave + fr;
; #pragma unroll
;             for (int nb = 0; nb < 8; ++nb) { const int col = g * 128 + 16 * nb + 4 * fq; const f32x4 o = acc[nb] * sc[nb];
;                 u32x2 w; w.x = pk2(o[0], o[1]); w.y = pk2(o[2], o[3]); *(u32x2*)(y + (size_t)row * DM + 512 + col) = w; }
	ds_read_b128 v[180:183], v187 offset:40960
	ds_read_b128 v[214:217], v207
	ds_read_b128 v[228:231], v207 offset:4352
	ds_read_b128 v[232:235], v207 offset:8704
	ds_read_b128 v[236:239], v207 offset:13056
	ds_read_b128 v[240:243], v207 offset:17408
	ds_read_b128 v[244:247], v207 offset:21760
	ds_read_b128 v[248:251], v207 offset:26112
	ds_read_b128 v[218:221], v207 offset:30464
	s_waitcnt lgkmcnt(7)
	v_mfma_f32_16x16x32_bf16 v[214:217], v[214:217], v[180:183], 0
	v_add_u32_e32 v2, s42, v186
	v_ashrrev_i32_e32 v3, 31, v2
	v_or_b32_e32 v1, s74, v184
	s_waitcnt lgkmcnt(6)
	v_mfma_f32_16x16x32_bf16 v[228:231], v[228:231], v[180:183], 0
	v_lshlrev_b64 v[2:3], 11, v[2:3]
	v_lshl_add_u64 v[2:3], s[28:29], 0, v[2:3]
	s_waitcnt lgkmcnt(5)
	v_mfma_f32_16x16x32_bf16 v[232:235], v[232:235], v[180:183], 0
	s_waitcnt lgkmcnt(4)
	v_mfma_f32_16x16x32_bf16 v[236:239], v[236:239], v[180:183], 0
	s_waitcnt lgkmcnt(3)
	v_mfma_f32_16x16x32_bf16 v[240:243], v[240:243], v[180:183], 0
	s_waitcnt lgkmcnt(2)
	v_mfma_f32_16x16x32_bf16 v[244:247], v[244:247], v[180:183], 0
	s_waitcnt lgkmcnt(1)
	v_mfma_f32_16x16x32_bf16 v[248:251], v[248:251], v[180:183], 0
	s_waitcnt lgkmcnt(0)
	v_mfma_f32_16x16x32_bf16 v[180:183], v[218:221], v[180:183], 0
	ds_read_b128 v[218:221], v187 offset:41024
	ds_read_b128 v[170:173], v207 offset:64
	s_waitcnt lgkmcnt(0)
	v_mfma_f32_16x16x32_bf16 v[170:173], v[170:173], v[218:221], v[214:217]
	s_nop 2
	ds_read_b128 v[214:217], v207 offset:4416
	s_waitcnt lgkmcnt(0)
	v_mfma_f32_16x16x32_bf16 v[214:217], v[214:217], v[218:221], v[228:231]
	s_nop 2
	ds_read_b128 v[228:231], v207 offset:8768
	s_waitcnt lgkmcnt(0)
	v_mfma_f32_16x16x32_bf16 v[228:231], v[228:231], v[218:221], v[232:235]
	s_nop 2
	ds_read_b128 v[232:235], v207 offset:13120
	s_waitcnt lgkmcnt(0)
	v_mfma_f32_16x16x32_bf16 v[232:235], v[232:235], v[218:221], v[236:239]
	s_nop 2
	ds_read_b128 v[236:239], v207 offset:17472
	s_waitcnt lgkmcnt(0)
	v_mfma_f32_16x16x32_bf16 v[236:239], v[236:239], v[218:221], v[240:243]
	s_nop 2
	ds_read_b128 v[240:243], v207 offset:21824
	s_waitcnt lgkmcnt(0)
	v_mfma_f32_16x16x32_bf16 v[240:243], v[240:243], v[218:221], v[244:247]
	s_nop 2
	ds_read_b128 v[244:247], v207 offset:26176
	s_waitcnt lgkmcnt(0)
	v_mfma_f32_16x16x32_bf16 v[244:247], v[244:247], v[218:221], v[248:251]
	s_nop 2
	ds_read_b128 v[248:251], v207 offset:30528
	s_waitcnt lgkmcnt(0)
	v_mfma_f32_16x16x32_bf16 v[180:183], v[248:251], v[218:221], v[180:183]
	ds_read_b128 v[218:221], v187 offset:41088
	ds_read_b128 v[248:251], v207 offset:128
	s_waitcnt lgkmcnt(0)
	v_mfma_f32_16x16x32_bf16 v[170:173], v[248:251], v[218:221], v[170:173]
	ds_read_b128 v[248:251], v207 offset:4480
	s_waitcnt lgkmcnt(0)
	v_mfma_f32_16x16x32_bf16 v[214:217], v[248:251], v[218:221], v[214:217]
	ds_read_b128 v[248:251], v207 offset:8832
	s_waitcnt lgkmcnt(0)
	v_mfma_f32_16x16x32_bf16 v[228:231], v[248:251], v[218:221], v[228:231]
	ds_read_b128 v[248:251], v207 offset:13184
	s_waitcnt lgkmcnt(0)
	v_mfma_f32_16x16x32_bf16 v[232:235], v[248:251], v[218:221], v[232:235]
	ds_read_b128 v[248:251], v207 offset:17536
	s_waitcnt lgkmcnt(0)
	v_mfma_f32_16x16x32_bf16 v[236:239], v[248:251], v[218:221], v[236:239]
	ds_read_b128 v[248:251], v207 offset:21888
	s_waitcnt lgkmcnt(0)
	v_mfma_f32_16x16x32_bf16 v[240:243], v[248:251], v[218:221], v[240:243]
	ds_read_b128 v[248:251], v207 offset:26240
	s_waitcnt lgkmcnt(0)
	v_mfma_f32_16x16x32_bf16 v[244:247], v[248:251], v[218:221], v[244:247]
	ds_read_b128 v[248:251], v207 offset:30592
	s_waitcnt lgkmcnt(0)
	v_mfma_f32_16x16x32_bf16 v[180:183], v[248:251], v[218:221], v[180:183]
	ds_read_b128 v[218:221], v187 offset:41152
	ds_read_b128 v[248:251], v207 offset:192
	s_waitcnt lgkmcnt(0)
	v_mfma_f32_16x16x32_bf16 v[170:173], v[248:251], v[218:221], v[170:173]
	ds_read_b128 v[248:251], v207 offset:4544
	s_waitcnt lgkmcnt(0)
	v_mfma_f32_16x16x32_bf16 v[214:217], v[248:251], v[218:221], v[214:217]
	ds_read_b128 v[248:251], v207 offset:8896
	s_waitcnt vmcnt(7)
	s_nop 2
	v_pk_mul_f32 v[118:119], v[118:119], v[172:173]
	v_pk_mul_f32 v[116:117], v[116:117], v[170:171]
	s_waitcnt lgkmcnt(0)
	v_mfma_f32_16x16x32_bf16 v[228:231], v[248:251], v[218:221], v[228:231]
	ds_read_b128 v[248:251], v207 offset:13248
	v_cvt_pk_bf16_f32 v116, v116, v117
	v_cvt_pk_bf16_f32 v117, v118, v119
	s_waitcnt lgkmcnt(0)
	v_mfma_f32_16x16x32_bf16 v[232:235], v[248:251], v[218:221], v[232:235]
	ds_read_b128 v[248:251], v207 offset:17600
	v_lshlrev_b32_e32 v118, 1, v1
	v_mov_b32_e32 v119, v0
	s_waitcnt lgkmcnt(0)
	v_mfma_f32_16x16x32_bf16 v[236:239], v[248:251], v[218:221], v[236:239]
	ds_read_b128 v[248:251], v207 offset:21952
	s_waitcnt vmcnt(6)
	v_pk_mul_f32 v[110:111], v[110:111], v[216:217]
	v_pk_mul_f32 v[108:109], v[108:109], v[214:215]
	s_waitcnt lgkmcnt(0)
	v_mfma_f32_16x16x32_bf16 v[240:243], v[248:251], v[218:221], v[240:243]
	ds_read_b128 v[248:251], v207 offset:26304
	s_waitcnt vmcnt(5)
	v_pk_mul_f32 v[106:107], v[106:107], v[230:231]
	v_pk_mul_f32 v[104:105], v[104:105], v[228:229]
	s_waitcnt lgkmcnt(0)
	v_mfma_f32_16x16x32_bf16 v[244:247], v[248:251], v[218:221], v[244:247]
	ds_read_b128 v[248:251], v207 offset:30656
	s_waitcnt vmcnt(4)
	v_pk_mul_f32 v[102:103], v[102:103], v[234:235]
	v_pk_mul_f32 v[100:101], v[100:101], v[232:233]
	s_waitcnt lgkmcnt(0)
	v_mfma_f32_16x16x32_bf16 v[180:183], v[248:251], v[218:221], v[180:183]
	s_waitcnt vmcnt(3)
	v_pk_mul_f32 v[98:99], v[98:99], v[238:239]
	v_pk_mul_f32 v[96:97], v[96:97], v[236:237]
	s_waitcnt vmcnt(2)
	v_pk_mul_f32 v[94:95], v[94:95], v[242:243]
	v_pk_mul_f32 v[92:93], v[92:93], v[240:241]
	s_waitcnt vmcnt(1)
	v_pk_mul_f32 v[90:91], v[90:91], v[246:247]
	v_pk_mul_f32 v[88:89], v[88:89], v[244:245]
	s_waitcnt vmcnt(0)
	v_pk_mul_f32 v[86:87], v[86:87], v[182:183]
	v_pk_mul_f32 v[84:85], v[84:85], v[180:181]
	v_lshl_add_u64 v[2:3], v[2:3], 0, v[118:119]
	v_cvt_pk_bf16_f32 v108, v108, v109
	v_cvt_pk_bf16_f32 v109, v110, v111
	v_cvt_pk_bf16_f32 v104, v104, v105
	v_cvt_pk_bf16_f32 v105, v106, v107
	v_cvt_pk_bf16_f32 v100, v100, v101
	v_cvt_pk_bf16_f32 v101, v102, v103
	v_cvt_pk_bf16_f32 v96, v96, v97
	v_cvt_pk_bf16_f32 v97, v98, v99
	v_cvt_pk_bf16_f32 v92, v92, v93
	v_cvt_pk_bf16_f32 v93, v94, v95
	v_cvt_pk_bf16_f32 v88, v88, v89
	v_cvt_pk_bf16_f32 v89, v90, v91
	v_cvt_pk_bf16_f32 v84, v84, v85
	v_cvt_pk_bf16_f32 v85, v86, v87
	global_store_dwordx2 v[2:3], v[116:117], off offset:1024 sc1
	global_store_dwordx2 v[2:3], v[108:109], off offset:1056 sc1
	global_store_dwordx2 v[2:3], v[104:105], off offset:1088 sc1
	global_store_dwordx2 v[2:3], v[100:101], off offset:1120 sc1
	global_store_dwordx2 v[2:3], v[96:97], off offset:1152 sc1
	global_store_dwordx2 v[2:3], v[92:93], off offset:1184 sc1
	global_store_dwordx2 v[2:3], v[88:89], off offset:1216 sc1
	global_store_dwordx2 v[2:3], v[84:85], off offset:1248 sc1
